# v020 plus FFN-down residual epilogue: next batch of base-tile loads issued before the current batch is consumed (two batches in flight)
# speedup vs baseline: 1.0147x; 1.0013x over previous
; #define PG8_STAGE(bufoff, gbase, voff) do { _Pragma("unroll") for (int _i = 0; _i < 2; ++_i) \
;         __builtin_amdgcn_global_load_lds((const unsigned*)((const char*)(gbase) + (voff)[_i]), (LAS unsigned*)(lds + (bufoff) + ldsw + _i * 8192), 16, 0, 0); } while (0)
; #define PG8_LDA(dst, b, h) do { _Pragma("unroll") for (int m = 0; m < 4; ++m) _Pragma("unroll") for (int k = 0; k < 2; ++k) dst[m][k] = *(const LAS bf16x8*)(lds + PG8_SA(b, h) + aoff + m * 2048 + k * 1024); } while (0)
; #define PG8_LDB(dst, b, h) do { _Pragma("unroll") for (int n = 0; n < 2; ++n) _Pragma("unroll") for (int k = 0; k < 2; ++k) dst[n][k] = *(const LAS bf16x8*)(lds + PG8_SB(b, h) + boff + n * 2048 + k * 1024); } while (0)
; #define PG8_MMA(ai, bj, At, Bt) do { __builtin_amdgcn_s_setprio(1); _Pragma("unroll") for (int m = 0; m < 4; ++m) _Pragma("unroll") for (int n = 0; n < 2; ++n) _Pragma("unroll") for (int k = 0; k < 2; ++k) \
;         acc[ai][bj][m][n] = __builtin_amdgcn_mfma_f32_16x16x32_bf16(Bt[n][k], At[m][k], acc[ai][bj][m][n], 0, 0, 0); __builtin_amdgcn_s_setprio(0); } while (0)
; #define PG8_WAIT_V(n) asm volatile("s_waitcnt vmcnt(" #n ")" ::: "memory")
; #define PG8_WAIT_L(n) asm volatile("s_waitcnt lgkmcnt(" #n ")" ::: "memory")
; #define PG8_BAR __builtin_amdgcn_s_barrier()
; #define PG8_SCHED __builtin_amdgcn_sched_barrier(0)
; template <class Epi, class Sched>
; __device__ __forceinline__ void gemm_phase(LAS unsigned char* lds, const Gemm g, const Sched S, const Epi E) {
;     ...
;             PG8_LDB(B0, 0, 0); PG8_SCHED; PG8_LDA(At, 0, 0); PG8_STAGE(PG8_SA(1, 1), a1 + hstep, voffA);
;             PG8_WAIT_L(8); PG8_BAR; PG8_WAIT_L(0); PG8_MMA(0, 0, At, B0); PG8_BAR; PG8_SCHED;
;             PG8_LDB(B1, 0, 1); PG8_STAGE(PG8_SB(0, 0), b2, voffB);
;             PG8_BAR; PG8_WAIT_L(0); PG8_MMA(0, 1, At, B1); PG8_BAR;
;             PG8_LDA(At, 0, 1); PG8_STAGE(PG8_SA(0, 0), a2, voffA);
;             PG8_BAR; PG8_WAIT_L(0); PG8_MMA(1, 0, At, B0); PG8_BAR; PG8_SCHED;
;             PG8_STAGE(PG8_SB(0, 1), b2 + hstep, voffB);
;             PG8_WAIT_V(6); PG8_BAR; PG8_MMA(1, 1, At, B1); PG8_BAR;
.LBB0_214:
	ds_read_b128 v[158:161], v154
	ds_read_b128 v[162:165], v154 offset:1024
	ds_read_b128 v[166:169], v154 offset:2048
	ds_read_b128 v[170:173], v154 offset:3072
	s_add_u32 s16, s12, 0xffea0080
	s_addc_u32 s17, s13, -1
	s_cmpk_eq_i32 s41, 0x54
	s_cselect_b32 s19, s7, s17
	s_cselect_b32 s18, s6, s16
	s_cselect_b32 s17, s1, s15
	s_cselect_b32 s16, s0, s14
	v_lshl_add_u64 v[142:143], s[12:13], 0, v[134:135]
	s_add_i32 m0, s22, 0xc000
	ds_read_b128 v[174:177], v155
	ds_read_b128 v[178:181], v155 offset:1024
	ds_read_b128 v[182:185], v155 offset:2048
	ds_read_b128 v[186:189], v155 offset:3072
	ds_read_b128 v[190:193], v155 offset:4096
	ds_read_b128 v[194:197], v155 offset:5120
	ds_read_b128 v[198:201], v155 offset:6144
	ds_read_b128 v[214:217], v155 offset:7168
	global_load_lds_dwordx4 v[142:143], off
	v_lshl_add_u64 v[142:143], s[12:13], 0, v[136:137]
	s_add_i32 m0, s22, 0xe000
	s_nop 0
	global_load_lds_dwordx4 v[142:143], off
	s_waitcnt lgkmcnt(8)
	s_barrier
	s_waitcnt lgkmcnt(0)
	s_setprio 1
	s_waitcnt lgkmcnt(0)
	v_mfma_f32_16x16x32_bf16 v[126:129], v[158:161], v[174:177], v[126:129]
	v_mfma_f32_16x16x32_bf16 v[122:125], v[166:169], v[174:177], v[122:125]
	v_mfma_f32_16x16x32_bf16 v[118:121], v[158:161], v[182:185], v[118:121]
	v_mfma_f32_16x16x32_bf16 v[114:117], v[166:169], v[182:185], v[114:117]
	v_mfma_f32_16x16x32_bf16 v[94:97], v[158:161], v[190:193], v[94:97]
	v_mfma_f32_16x16x32_bf16 v[90:93], v[166:169], v[190:193], v[90:93]
	v_mfma_f32_16x16x32_bf16 v[86:89], v[158:161], v[198:201], v[86:89]
	v_mfma_f32_16x16x32_bf16 v[82:85], v[166:169], v[198:201], v[82:85]
	v_mfma_f32_16x16x32_bf16 v[126:129], v[162:165], v[178:181], v[126:129]
	v_mfma_f32_16x16x32_bf16 v[122:125], v[170:173], v[178:181], v[122:125]
	v_mfma_f32_16x16x32_bf16 v[118:121], v[162:165], v[186:189], v[118:121]
	v_mfma_f32_16x16x32_bf16 v[114:117], v[170:173], v[186:189], v[114:117]
	v_mfma_f32_16x16x32_bf16 v[94:97], v[162:165], v[194:197], v[94:97]
	v_mfma_f32_16x16x32_bf16 v[90:93], v[170:173], v[194:197], v[90:93]
	v_mfma_f32_16x16x32_bf16 v[86:89], v[162:165], v[214:217], v[86:89]
	s_barrier
	v_mfma_f32_16x16x32_bf16 v[82:85], v[170:173], v[214:217], v[82:85]
	s_setprio 0
	s_add_i32 s48, s34, s20
	v_lshl_add_u64 v[142:143], s[16:17], 0, v[130:131]
	s_mov_b32 m0, s48
	ds_read_b128 v[218:221], v156
	ds_read_b128 v[222:225], v156 offset:1024
	ds_read_b128 v[226:229], v156 offset:2048
	ds_read_b128 v[230:233], v156 offset:3072
	global_load_lds_dwordx4 v[142:143], off
	v_lshl_add_u64 v[202:203], s[16:17], 0, v[132:133]
	s_add_i32 m0, s48, 0x2000
	s_nop 0
	global_load_lds_dwordx4 v[202:203], off
	s_barrier
	s_waitcnt lgkmcnt(0)
	s_setprio 1
	s_waitcnt lgkmcnt(0)
	v_mfma_f32_16x16x32_bf16 v[110:113], v[218:221], v[174:177], v[110:113]
	v_mfma_f32_16x16x32_bf16 v[106:109], v[226:229], v[174:177], v[106:109]
	v_mfma_f32_16x16x32_bf16 v[102:105], v[218:221], v[182:185], v[102:105]
	v_mfma_f32_16x16x32_bf16 v[98:101], v[226:229], v[182:185], v[98:101]
	v_mfma_f32_16x16x32_bf16 v[78:81], v[218:221], v[190:193], v[78:81]
	v_mfma_f32_16x16x32_bf16 v[74:77], v[226:229], v[190:193], v[74:77]
	v_mfma_f32_16x16x32_bf16 v[70:73], v[218:221], v[198:201], v[70:73]
	v_mfma_f32_16x16x32_bf16 v[66:69], v[226:229], v[198:201], v[66:69]
	v_mfma_f32_16x16x32_bf16 v[110:113], v[222:225], v[178:181], v[110:113]
	v_mfma_f32_16x16x32_bf16 v[106:109], v[230:233], v[178:181], v[106:109]
	v_mfma_f32_16x16x32_bf16 v[102:105], v[222:225], v[186:189], v[102:105]
	v_mfma_f32_16x16x32_bf16 v[98:101], v[230:233], v[186:189], v[98:101]
	v_mfma_f32_16x16x32_bf16 v[78:81], v[222:225], v[194:197], v[78:81]
	v_mfma_f32_16x16x32_bf16 v[74:77], v[230:233], v[194:197], v[74:77]
	v_mfma_f32_16x16x32_bf16 v[70:73], v[222:225], v[214:217], v[70:73]
	s_barrier
	v_mfma_f32_16x16x32_bf16 v[66:69], v[230:233], v[214:217], v[66:69]
	s_setprio 0
	s_mov_b32 m0, s22
	v_lshl_add_u64 v[206:207], s[18:19], 0, v[130:131]
	ds_read_b128 v[174:177], v155 offset:16384
	ds_read_b128 v[178:181], v155 offset:17408
	ds_read_b128 v[182:185], v155 offset:18432
	ds_read_b128 v[186:189], v155 offset:19456
	ds_read_b128 v[190:193], v155 offset:20480
	ds_read_b128 v[194:197], v155 offset:21504
	ds_read_b128 v[198:201], v155 offset:22528
	ds_read_b128 v[214:217], v155 offset:23552
	global_load_lds_dwordx4 v[206:207], off
	v_lshl_add_u64 v[234:235], s[18:19], 0, v[132:133]
	s_mov_b32 m0, s23
	s_nop 0
	global_load_lds_dwordx4 v[234:235], off
	s_barrier
	s_waitcnt lgkmcnt(0)
	s_setprio 1
	s_waitcnt lgkmcnt(0)
	v_mfma_f32_16x16x32_bf16 v[62:65], v[158:161], v[174:177], v[62:65]
	v_mfma_f32_16x16x32_bf16 v[58:61], v[166:169], v[174:177], v[58:61]
	v_mfma_f32_16x16x32_bf16 v[54:57], v[158:161], v[182:185], v[54:57]
	v_mfma_f32_16x16x32_bf16 v[50:53], v[166:169], v[182:185], v[50:53]
	v_mfma_f32_16x16x32_bf16 v[30:33], v[158:161], v[190:193], v[30:33]
	v_mfma_f32_16x16x32_bf16 v[26:29], v[166:169], v[190:193], v[26:29]
	v_mfma_f32_16x16x32_bf16 v[22:25], v[158:161], v[198:201], v[22:25]
	v_mfma_f32_16x16x32_bf16 v[18:21], v[166:169], v[198:201], v[18:21]
	v_mfma_f32_16x16x32_bf16 v[62:65], v[162:165], v[178:181], v[62:65]
	v_mfma_f32_16x16x32_bf16 v[58:61], v[170:173], v[178:181], v[58:61]
	v_mfma_f32_16x16x32_bf16 v[54:57], v[162:165], v[186:189], v[54:57]
	v_mfma_f32_16x16x32_bf16 v[50:53], v[170:173], v[186:189], v[50:53]
	v_mfma_f32_16x16x32_bf16 v[30:33], v[162:165], v[194:197], v[30:33]
	v_mfma_f32_16x16x32_bf16 v[26:29], v[170:173], v[194:197], v[26:29]
	v_mfma_f32_16x16x32_bf16 v[22:25], v[162:165], v[214:217], v[22:25]
	s_barrier
; #define PG8_STAGE(bufoff, gbase, voff) do { _Pragma("unroll") for (int _i = 0; _i < 2; ++_i) \
;         __builtin_amdgcn_global_load_lds((const unsigned*)((const char*)(gbase) + (voff)[_i]), (LAS unsigned*)(lds + (bufoff) + ldsw + _i * 8192), 16, 0, 0); } while (0)
; #define PG8_LDA(dst, b, h) do { _Pragma("unroll") for (int m = 0; m < 4; ++m) _Pragma("unroll") for (int k = 0; k < 2; ++k) dst[m][k] = *(const LAS bf16x8*)(lds + PG8_SA(b, h) + aoff + m * 2048 + k * 1024); } while (0)
; #define PG8_LDB(dst, b, h) do { _Pragma("unroll") for (int n = 0; n < 2; ++n) _Pragma("unroll") for (int k = 0; k < 2; ++k) dst[n][k] = *(const LAS bf16x8*)(lds + PG8_SB(b, h) + boff + n * 2048 + k * 1024); } while (0)
; #define PG8_MMA(ai, bj, At, Bt) do { __builtin_amdgcn_s_setprio(1); _Pragma("unroll") for (int m = 0; m < 4; ++m) _Pragma("unroll") for (int n = 0; n < 2; ++n) _Pragma("unroll") for (int k = 0; k < 2; ++k) \
;         acc[ai][bj][m][n] = __builtin_amdgcn_mfma_f32_16x16x32_bf16(Bt[n][k], At[m][k], acc[ai][bj][m][n], 0, 0, 0); __builtin_amdgcn_s_setprio(0); } while (0)
; #define PG8_WAIT_V(n) asm volatile("s_waitcnt vmcnt(" #n ")" ::: "memory")
; #define PG8_WAIT_L(n) asm volatile("s_waitcnt lgkmcnt(" #n ")" ::: "memory")
; #define PG8_BAR __builtin_amdgcn_s_barrier()
; #define PG8_SCHED __builtin_amdgcn_sched_barrier(0)
; template <class Epi, class Sched>
; __device__ __forceinline__ void gemm_phase(LAS unsigned char* lds, const Gemm g, const Sched S, const Epi E) {
;     ...
;             PG8_BAR; PG8_WAIT_L(0); PG8_MMA(1, 0, At, B0); PG8_BAR; PG8_SCHED;
;             PG8_STAGE(PG8_SB(0, 1), b2 + hstep, voffB);
;             PG8_WAIT_V(6); PG8_BAR; PG8_MMA(1, 1, At, B1); PG8_BAR;
;             PG8_LDB(B0, 1, 0); PG8_SCHED; PG8_LDA(At, 1, 0); PG8_STAGE(PG8_SA(0, 1), a2 + hstep, voffA);
;             PG8_WAIT_L(8); PG8_BAR; PG8_WAIT_L(0); PG8_MMA(0, 0, At, B0); PG8_BAR; PG8_SCHED;
;             PG8_LDB(B1, 1, 1); PG8_STAGE(PG8_SB(1, 0), b3, voffB);
;             PG8_BAR; PG8_WAIT_L(0); PG8_MMA(0, 1, At, B1); PG8_BAR;
;             PG8_LDA(At, 1, 1); PG8_STAGE(PG8_SA(1, 0), a3, voffA);
;             PG8_BAR; PG8_WAIT_L(0); PG8_MMA(1, 0, At, B0); PG8_BAR; PG8_SCHED;
	v_mfma_f32_16x16x32_bf16 v[18:21], v[170:173], v[214:217], v[18:21]
	s_setprio 0
	s_add_u32 s48, s16, 0x160000
	s_addc_u32 s49, s17, 0
	s_add_i32 s50, s35, s20
	v_lshl_add_u64 v[158:159], s[48:49], 0, v[130:131]
	s_mov_b32 m0, s50
	s_nop 0
	global_load_lds_dwordx4 v[158:159], off
	v_lshl_add_u64 v[158:159], s[48:49], 0, v[132:133]
	s_add_i32 m0, s50, 0x2000
	s_nop 0
	global_load_lds_dwordx4 v[158:159], off
	s_waitcnt vmcnt(6)
	s_barrier
	s_setprio 1
	v_mfma_f32_16x16x32_bf16 v[46:49], v[218:221], v[174:177], v[46:49]
	v_mfma_f32_16x16x32_bf16 v[42:45], v[226:229], v[174:177], v[42:45]
	v_mfma_f32_16x16x32_bf16 v[38:41], v[218:221], v[182:185], v[38:41]
	v_mfma_f32_16x16x32_bf16 v[34:37], v[226:229], v[182:185], v[34:37]
	v_mfma_f32_16x16x32_bf16 v[14:17], v[218:221], v[190:193], v[14:17]
	v_mfma_f32_16x16x32_bf16 v[10:13], v[226:229], v[190:193], v[10:13]
	v_mfma_f32_16x16x32_bf16 v[6:9], v[218:221], v[198:201], v[6:9]
	v_mfma_f32_16x16x32_bf16 v[2:5], v[226:229], v[198:201], v[2:5]
	v_mfma_f32_16x16x32_bf16 v[46:49], v[222:225], v[178:181], v[46:49]
	v_mfma_f32_16x16x32_bf16 v[42:45], v[230:233], v[178:181], v[42:45]
	v_mfma_f32_16x16x32_bf16 v[38:41], v[222:225], v[186:189], v[38:41]
	v_mfma_f32_16x16x32_bf16 v[34:37], v[230:233], v[186:189], v[34:37]
	v_mfma_f32_16x16x32_bf16 v[14:17], v[222:225], v[194:197], v[14:17]
	v_mfma_f32_16x16x32_bf16 v[10:13], v[230:233], v[194:197], v[10:13]
	v_mfma_f32_16x16x32_bf16 v[6:9], v[222:225], v[214:217], v[6:9]
	s_barrier
	v_mfma_f32_16x16x32_bf16 v[2:5], v[230:233], v[214:217], v[2:5]
	s_setprio 0
	s_add_i32 s48, 0, 0x18000
	v_add_u32_e32 v157, s48, v152
	ds_read_b128 v[158:161], v157
	ds_read_b128 v[162:165], v157 offset:1024
	ds_read_b128 v[166:169], v157 offset:2048
	ds_read_b128 v[170:173], v157 offset:3072
	s_add_u32 s18, s18, 0x160000
	s_addc_u32 s19, s19, 0
	s_mov_b32 m0, s24
	v_lshl_add_u64 v[218:219], s[18:19], 0, v[130:131]
	ds_read_b128 v[174:177], v155 offset:32768
	ds_read_b128 v[178:181], v155 offset:33792
	ds_read_b128 v[182:185], v155 offset:34816
	ds_read_b128 v[186:189], v155 offset:35840
	ds_read_b128 v[190:193], v155 offset:36864
	ds_read_b128 v[194:197], v155 offset:37888
	ds_read_b128 v[198:201], v155 offset:38912
	ds_read_b128 v[214:217], v155 offset:39936
	global_load_lds_dwordx4 v[218:219], off
	v_lshl_add_u64 v[218:219], s[18:19], 0, v[132:133]
	s_mov_b32 m0, s25
	s_nop 0
	global_load_lds_dwordx4 v[218:219], off
	s_waitcnt lgkmcnt(8)
	s_barrier
	s_waitcnt lgkmcnt(0)
	s_setprio 1
	s_waitcnt lgkmcnt(0)
	v_mfma_f32_16x16x32_bf16 v[126:129], v[158:161], v[174:177], v[126:129]
	v_mfma_f32_16x16x32_bf16 v[122:125], v[166:169], v[174:177], v[122:125]
	v_mfma_f32_16x16x32_bf16 v[118:121], v[158:161], v[182:185], v[118:121]
	v_mfma_f32_16x16x32_bf16 v[114:117], v[166:169], v[182:185], v[114:117]
	v_mfma_f32_16x16x32_bf16 v[94:97], v[158:161], v[190:193], v[94:97]
	v_mfma_f32_16x16x32_bf16 v[90:93], v[166:169], v[190:193], v[90:93]
	v_mfma_f32_16x16x32_bf16 v[86:89], v[158:161], v[198:201], v[86:89]
	v_mfma_f32_16x16x32_bf16 v[82:85], v[166:169], v[198:201], v[82:85]
	v_mfma_f32_16x16x32_bf16 v[126:129], v[162:165], v[178:181], v[126:129]
	v_mfma_f32_16x16x32_bf16 v[122:125], v[170:173], v[178:181], v[122:125]
	v_mfma_f32_16x16x32_bf16 v[118:121], v[162:165], v[186:189], v[118:121]
	v_mfma_f32_16x16x32_bf16 v[114:117], v[170:173], v[186:189], v[114:117]
	v_mfma_f32_16x16x32_bf16 v[94:97], v[162:165], v[194:197], v[94:97]
	v_mfma_f32_16x16x32_bf16 v[90:93], v[170:173], v[194:197], v[90:93]
	v_mfma_f32_16x16x32_bf16 v[86:89], v[162:165], v[214:217], v[86:89]
	s_barrier
	v_mfma_f32_16x16x32_bf16 v[82:85], v[170:173], v[214:217], v[82:85]
	s_setprio 0
	s_add_i32 s18, 0, 0x1c000
	s_add_i32 s19, s48, s20
	v_add_u32_e32 v157, s18, v152
	v_lshl_add_u64 v[142:143], v[142:143], 0, s[10:11]
	s_mov_b32 m0, s19
	ds_read_b128 v[218:221], v157
	ds_read_b128 v[222:225], v157 offset:1024
	ds_read_b128 v[226:229], v157 offset:2048
	ds_read_b128 v[230:233], v157 offset:3072
	global_load_lds_dwordx4 v[142:143], off
	v_lshl_add_u64 v[142:143], v[202:203], 0, s[10:11]
	s_add_i32 m0, s19, 0x2000
	s_nop 0
	global_load_lds_dwordx4 v[142:143], off
	s_barrier
	s_waitcnt lgkmcnt(0)
	s_setprio 1
	s_waitcnt lgkmcnt(0)
	v_mfma_f32_16x16x32_bf16 v[110:113], v[218:221], v[174:177], v[110:113]
	v_mfma_f32_16x16x32_bf16 v[106:109], v[226:229], v[174:177], v[106:109]
	v_mfma_f32_16x16x32_bf16 v[102:105], v[218:221], v[182:185], v[102:105]
	v_mfma_f32_16x16x32_bf16 v[98:101], v[226:229], v[182:185], v[98:101]
	v_mfma_f32_16x16x32_bf16 v[78:81], v[218:221], v[190:193], v[78:81]
	v_mfma_f32_16x16x32_bf16 v[74:77], v[226:229], v[190:193], v[74:77]
	v_mfma_f32_16x16x32_bf16 v[70:73], v[218:221], v[198:201], v[70:73]
	v_mfma_f32_16x16x32_bf16 v[66:69], v[226:229], v[198:201], v[66:69]
	v_mfma_f32_16x16x32_bf16 v[110:113], v[222:225], v[178:181], v[110:113]
	v_mfma_f32_16x16x32_bf16 v[106:109], v[230:233], v[178:181], v[106:109]
	v_mfma_f32_16x16x32_bf16 v[102:105], v[222:225], v[186:189], v[102:105]
	v_mfma_f32_16x16x32_bf16 v[98:101], v[230:233], v[186:189], v[98:101]
	v_mfma_f32_16x16x32_bf16 v[78:81], v[222:225], v[194:197], v[78:81]
	v_mfma_f32_16x16x32_bf16 v[74:77], v[230:233], v[194:197], v[74:77]
	v_mfma_f32_16x16x32_bf16 v[70:73], v[222:225], v[214:217], v[70:73]
	s_barrier
	v_mfma_f32_16x16x32_bf16 v[66:69], v[230:233], v[214:217], v[66:69]
	s_setprio 0
	s_mov_b32 m0, s30
	v_lshl_add_u64 v[142:143], v[206:207], 0, s[10:11]
	ds_read_b128 v[174:177], v155 offset:49152
	ds_read_b128 v[178:181], v155 offset:50176
	ds_read_b128 v[182:185], v155 offset:51200
	ds_read_b128 v[186:189], v155 offset:52224
	ds_read_b128 v[190:193], v155 offset:53248
	ds_read_b128 v[194:197], v155 offset:54272
	ds_read_b128 v[198:201], v155 offset:55296
	ds_read_b128 v[214:217], v155 offset:56320
	global_load_lds_dwordx4 v[142:143], off
	v_lshl_add_u64 v[142:143], v[234:235], 0, s[10:11]
	s_mov_b32 m0, s31
	s_nop 0
	global_load_lds_dwordx4 v[142:143], off
	s_barrier
; #define PG8_STAGE(bufoff, gbase, voff) do { _Pragma("unroll") for (int _i = 0; _i < 2; ++_i) \
;         __builtin_amdgcn_global_load_lds((const unsigned*)((const char*)(gbase) + (voff)[_i]), (LAS unsigned*)(lds + (bufoff) + ldsw + _i * 8192), 16, 0, 0); } while (0)
; #define PG8_LDA(dst, b, h) do { _Pragma("unroll") for (int m = 0; m < 4; ++m) _Pragma("unroll") for (int k = 0; k < 2; ++k) dst[m][k] = *(const LAS bf16x8*)(lds + PG8_SA(b, h) + aoff + m * 2048 + k * 1024); } while (0)
; #define PG8_MMA(ai, bj, At, Bt) do { __builtin_amdgcn_s_setprio(1); _Pragma("unroll") for (int m = 0; m < 4; ++m) _Pragma("unroll") for (int n = 0; n < 2; ++n) _Pragma("unroll") for (int k = 0; k < 2; ++k) \
;         acc[ai][bj][m][n] = __builtin_amdgcn_mfma_f32_16x16x32_bf16(Bt[n][k], At[m][k], acc[ai][bj][m][n], 0, 0, 0); __builtin_amdgcn_s_setprio(0); } while (0)
; #define PG8_WAIT_V(n) asm volatile("s_waitcnt vmcnt(" #n ")" ::: "memory")
; #define PG8_WAIT_L(n) asm volatile("s_waitcnt lgkmcnt(" #n ")" ::: "memory")
; #define PG8_BAR __builtin_amdgcn_s_barrier()
; #define PG8_SCHED __builtin_amdgcn_sched_barrier(0)
; template <class Epi, class Sched>
; __device__ __forceinline__ void gemm_phase(LAS unsigned char* lds, const Gemm g, const Sched S, const Epi E) {
;     ...
;             PG8_LDA(At, 1, 1); PG8_STAGE(PG8_SA(1, 0), a3, voffA);
;             PG8_BAR; PG8_WAIT_L(0); PG8_MMA(1, 0, At, B0); PG8_BAR; PG8_SCHED;
;             PG8_STAGE(PG8_SB(1, 1), b3 + hstep, voffB);
;             PG8_WAIT_V(6); PG8_BAR; PG8_MMA(1, 1, At, B1); PG8_BAR;
;         }
;     __device__ __forceinline__ void operator()(const f32x4 (&acc)[2][2][4][2], const Unit& u, int wr, int wc, int fr, int fq) const {
;         const int row0 = u.pm * 256 + wr * 64 + fr, col0 = u.pn * 256 + wc * 32 + 4 * fq;
; #pragma unroll
;         for (int ai = 0; ai < 2; ++ai)
; #pragma unroll
;             for (int mp = 0; mp < 4; mp += 2) {
;                 f32x4 bv[2][2][2];
; #pragma unroll
;                 for (int m = 0; m < 2; ++m) { const int off = (row0 + ai * HALF + (mp + m) * 16) * DM + col0;
; #pragma unroll
;                     for (int bj = 0; bj < 2; ++bj)
; #pragma unroll
;                         for (int n = 0; n < 2; ++n) bv[m][bj][n] = *(const f32x4*)(base + off + bj * HALF + n * 16); }
	s_waitcnt lgkmcnt(0)
	s_setprio 1
	s_waitcnt lgkmcnt(0)
	v_mfma_f32_16x16x32_bf16 v[62:65], v[158:161], v[174:177], v[62:65]
	v_mfma_f32_16x16x32_bf16 v[58:61], v[166:169], v[174:177], v[58:61]
	v_mfma_f32_16x16x32_bf16 v[54:57], v[158:161], v[182:185], v[54:57]
	v_mfma_f32_16x16x32_bf16 v[50:53], v[166:169], v[182:185], v[50:53]
	v_mfma_f32_16x16x32_bf16 v[30:33], v[158:161], v[190:193], v[30:33]
	v_mfma_f32_16x16x32_bf16 v[26:29], v[166:169], v[190:193], v[26:29]
	v_mfma_f32_16x16x32_bf16 v[22:25], v[158:161], v[198:201], v[22:25]
	v_mfma_f32_16x16x32_bf16 v[18:21], v[166:169], v[198:201], v[18:21]
	v_mfma_f32_16x16x32_bf16 v[62:65], v[162:165], v[178:181], v[62:65]
	v_mfma_f32_16x16x32_bf16 v[58:61], v[170:173], v[178:181], v[58:61]
	v_mfma_f32_16x16x32_bf16 v[54:57], v[162:165], v[186:189], v[54:57]
	v_mfma_f32_16x16x32_bf16 v[50:53], v[170:173], v[186:189], v[50:53]
	v_mfma_f32_16x16x32_bf16 v[30:33], v[162:165], v[194:197], v[30:33]
	v_mfma_f32_16x16x32_bf16 v[26:29], v[170:173], v[194:197], v[26:29]
	v_mfma_f32_16x16x32_bf16 v[22:25], v[162:165], v[214:217], v[22:25]
	s_barrier
	v_mfma_f32_16x16x32_bf16 v[18:21], v[170:173], v[214:217], v[18:21]
	s_setprio 0
	s_add_u32 s16, s16, 0x160080
	s_addc_u32 s17, s17, 0
	s_add_i32 s18, s18, s20
	v_lshl_add_u64 v[142:143], s[16:17], 0, v[130:131]
	s_mov_b32 m0, s18
	s_nop 0
	global_load_lds_dwordx4 v[142:143], off
	v_lshl_add_u64 v[142:143], s[16:17], 0, v[132:133]
	s_add_i32 m0, s18, 0x2000
	s_nop 0
	global_load_lds_dwordx4 v[142:143], off
	s_waitcnt vmcnt(6)
	s_barrier
	s_setprio 1
	v_mfma_f32_16x16x32_bf16 v[46:49], v[218:221], v[174:177], v[46:49]
	v_mfma_f32_16x16x32_bf16 v[42:45], v[226:229], v[174:177], v[42:45]
	v_mfma_f32_16x16x32_bf16 v[38:41], v[218:221], v[182:185], v[38:41]
	v_mfma_f32_16x16x32_bf16 v[34:37], v[226:229], v[182:185], v[34:37]
	v_mfma_f32_16x16x32_bf16 v[14:17], v[218:221], v[190:193], v[14:17]
	v_mfma_f32_16x16x32_bf16 v[10:13], v[226:229], v[190:193], v[10:13]
	v_mfma_f32_16x16x32_bf16 v[6:9], v[218:221], v[198:201], v[6:9]
	v_mfma_f32_16x16x32_bf16 v[2:5], v[226:229], v[198:201], v[2:5]
	v_mfma_f32_16x16x32_bf16 v[46:49], v[222:225], v[178:181], v[46:49]
	v_mfma_f32_16x16x32_bf16 v[42:45], v[230:233], v[178:181], v[42:45]
	v_mfma_f32_16x16x32_bf16 v[38:41], v[222:225], v[186:189], v[38:41]
	v_mfma_f32_16x16x32_bf16 v[34:37], v[230:233], v[186:189], v[34:37]
	v_mfma_f32_16x16x32_bf16 v[14:17], v[222:225], v[194:197], v[14:17]
	v_mfma_f32_16x16x32_bf16 v[10:13], v[230:233], v[194:197], v[10:13]
	v_mfma_f32_16x16x32_bf16 v[6:9], v[222:225], v[214:217], v[6:9]
	s_barrier
	v_mfma_f32_16x16x32_bf16 v[2:5], v[230:233], v[214:217], v[2:5]
	s_setprio 0
	s_add_i32 s41, s41, 2
	s_add_u32 s12, s12, 0x100
	s_addc_u32 s13, s13, 0
	s_add_u32 s14, s14, 0x100
	s_addc_u32 s15, s15, 0
	s_cmpk_gt_u32 s41, 0x55
	s_cbranch_scc0 .LBB0_214
	s_lshl_b32 s2, s2, 8
	s_lshl_b32 s12, s40, 19
	s_add_i32 s12, s12, s2
	v_add_u32_e32 v142, s12, v153
	v_ashrrev_i32_e32 v143, 31, v142
	v_lshl_add_u64 v[170:171], v[142:143], 2, s[36:37]
	v_add_u32_e32 v190, 0x8000, v142
	global_load_dwordx4 v[158:161], v[170:171], off
	global_load_dwordx4 v[162:165], v[170:171], off offset:64
	global_load_dwordx4 v[166:169], v[170:171], off offset:512
	s_nop 0
	global_load_dwordx4 v[170:173], v[170:171], off offset:576
	v_ashrrev_i32_e32 v191, 31, v190
	v_lshl_add_u64 v[186:187], v[190:191], 2, s[36:37]
	global_load_dwordx4 v[174:177], v[186:187], off
	global_load_dwordx4 v[178:181], v[186:187], off offset:64
	global_load_dwordx4 v[182:185], v[186:187], off offset:512
	s_nop 0
	global_load_dwordx4 v[186:189], v[186:187], off offset:576
	v_lshl_add_u64 v[194:195], v[142:143], 1, s[74:75]
	v_add_u32_e32 v192, 0x10000, v142
	v_lshl_add_u64 v[190:191], v[190:191], 1, s[74:75]
	v_ashrrev_i32_e32 v193, 31, v192
	v_lshl_add_u64 v[196:197], v[192:193], 2, s[36:37]
	s_and_b64 vcc, exec, s[4:5]
	s_mov_b32 s2, s38
	s_mov_b32 s40, s39
	s_mov_b64 s[16:17], s[0:1]
	s_mov_b64 s[12:13], s[6:7]
	v_add_u32_e32 v250, 0x18000, v142
	v_ashrrev_i32_e32 v251, 31, v250
	v_lshl_add_u64 v[250:251], v[250:251], 2, s[36:37]
	global_load_dwordx4 v[214:217], v[196:197], off
	global_load_dwordx4 v[218:221], v[196:197], off offset:64
	global_load_dwordx4 v[222:225], v[196:197], off offset:512
	global_load_dwordx4 v[226:229], v[196:197], off offset:576
	global_load_dwordx4 v[230:233], v[250:251], off
	global_load_dwordx4 v[234:237], v[250:251], off offset:64
	global_load_dwordx4 v[238:241], v[250:251], off offset:512
	global_load_dwordx4 v[246:249], v[250:251], off offset:576
	s_waitcnt vmcnt(8)
; __device__ __forceinline__ unsigned cvtpk(float lo, float hi) { unsigned r; asm volatile("v_cvt_pk_bf16_f32 %0, %1, %2" : "=v"(r) : "v"(lo), "v"(hi)); return r; }
;     __device__ __forceinline__ void operator()(const f32x4 (&acc)[2][2][4][2], const Unit& u, int wr, int wc, int fr, int fq) const {
;         const int row0 = u.pm * 256 + wr * 64 + fr, col0 = u.pn * 256 + wc * 32 + 4 * fq;
; #pragma unroll
;         for (int ai = 0; ai < 2; ++ai)
; #pragma unroll
;             for (int mp = 0; mp < 4; mp += 2) {
;                 f32x4 bv[2][2][2];
; #pragma unroll
;                 for (int m = 0; m < 2; ++m) { const int off = (row0 + ai * HALF + (mp + m) * 16) * DM + col0;
; #pragma unroll
;                     for (int bj = 0; bj < 2; ++bj)
; #pragma unroll
;                         for (int n = 0; n < 2; ++n) bv[m][bj][n] = *(const f32x4*)(base + off + bj * HALF + n * 16); }
; #pragma unroll
;                 for (int m = 0; m < 2; ++m) { const int off = (row0 + ai * HALF + (mp + m) * 16) * DM + col0;
; #pragma unroll
;                     for (int bj = 0; bj < 2; ++bj)
; #pragma unroll
;                         for (int n = 0; n < 2; ++n) { const f32x4 v = bv[m][bj][n] + acc[ai][bj][mp + m][n] * s;
;                             u32x2 w; w.x = cvtpk(v[0], v[1]); w.y = cvtpk(v[2], v[3]); *(u32x2*)(xb + off + bj * HALF + n * 16) = w; } }
;                 asm volatile("" ::: "memory"); }
	v_pk_fma_f32 v[126:127], v[126:127], 0.5, v[158:159] op_sel_hi:[1,0,1]
	v_pk_fma_f32 v[122:123], v[122:123], 0.5, v[162:163] op_sel_hi:[1,0,1]
	v_pk_fma_f32 v[110:111], v[110:111], 0.5, v[166:167] op_sel_hi:[1,0,1]
	v_pk_fma_f32 v[106:107], v[106:107], 0.5, v[170:171] op_sel_hi:[1,0,1]
	v_pk_fma_f32 v[128:129], v[128:129], 0.5, v[160:161] op_sel_hi:[1,0,1]
	v_pk_fma_f32 v[124:125], v[124:125], 0.5, v[164:165] op_sel_hi:[1,0,1]
	v_pk_fma_f32 v[112:113], v[112:113], 0.5, v[168:169] op_sel_hi:[1,0,1]
	v_pk_fma_f32 v[108:109], v[108:109], 0.5, v[172:173] op_sel_hi:[1,0,1]
	v_cvt_pk_bf16_f32 v126, v126, v127
	v_cvt_pk_bf16_f32 v127, v128, v129
	global_store_dwordx2 v[194:195], v[126:127], off
	v_cvt_pk_bf16_f32 v122, v122, v123
	v_cvt_pk_bf16_f32 v123, v124, v125
	global_store_dwordx2 v[194:195], v[122:123], off offset:32
	v_cvt_pk_bf16_f32 v110, v110, v111
	v_cvt_pk_bf16_f32 v111, v112, v113
	global_store_dwordx2 v[194:195], v[110:111], off offset:256
	v_cvt_pk_bf16_f32 v106, v106, v107
	v_cvt_pk_bf16_f32 v107, v108, v109
	v_pk_fma_f32 v[120:121], v[120:121], 0.5, v[176:177] op_sel_hi:[1,0,1]
	v_pk_fma_f32 v[118:119], v[118:119], 0.5, v[174:175] op_sel_hi:[1,0,1]
	v_pk_fma_f32 v[102:103], v[102:103], 0.5, v[182:183] op_sel_hi:[1,0,1]
	v_pk_fma_f32 v[98:99], v[98:99], 0.5, v[186:187] op_sel_hi:[1,0,1]
	global_store_dwordx2 v[194:195], v[106:107], off offset:288
	v_cvt_pk_bf16_f32 v106, v118, v119
	v_cvt_pk_bf16_f32 v107, v120, v121
	v_pk_fma_f32 v[116:117], v[116:117], 0.5, v[180:181] op_sel_hi:[1,0,1]
	v_pk_fma_f32 v[114:115], v[114:115], 0.5, v[178:179] op_sel_hi:[1,0,1]
	v_pk_fma_f32 v[104:105], v[104:105], 0.5, v[184:185] op_sel_hi:[1,0,1]
	v_pk_fma_f32 v[100:101], v[100:101], 0.5, v[188:189] op_sel_hi:[1,0,1]
	global_store_dwordx2 v[190:191], v[106:107], off
	v_cvt_pk_bf16_f32 v106, v114, v115
	v_cvt_pk_bf16_f32 v107, v116, v117
	global_store_dwordx2 v[190:191], v[106:107], off offset:32
	v_cvt_pk_bf16_f32 v102, v102, v103
	v_cvt_pk_bf16_f32 v103, v104, v105
	global_store_dwordx2 v[190:191], v[102:103], off offset:256
	v_cvt_pk_bf16_f32 v98, v98, v99
	v_cvt_pk_bf16_f32 v99, v100, v101
	global_store_dwordx2 v[190:191], v[98:99], off offset:288
	v_add_u32_e32 v158, 0x18000, v142
	v_ashrrev_i32_e32 v159, 31, v158
	v_lshl_add_u64 v[126:127], v[158:159], 2, s[36:37]
	s_nop 0
	v_lshl_add_u64 v[162:163], v[192:193], 1, s[74:75]
	v_add_u32_e32 v160, 0x40000, v142
	v_lshl_add_u64 v[158:159], v[158:159], 1, s[74:75]
	v_ashrrev_i32_e32 v161, 31, v160
	v_lshl_add_u64 v[164:165], v[160:161], 2, s[36:37]
	s_waitcnt vmcnt(8)
	v_pk_fma_f32 v[94:95], v[94:95], 0.5, v[214:215] op_sel_hi:[1, 0, 1]
	v_pk_fma_f32 v[90:91], v[90:91], 0.5, v[218:219] op_sel_hi:[1, 0, 1]
	v_pk_fma_f32 v[78:79], v[78:79], 0.5, v[222:223] op_sel_hi:[1, 0, 1]
	v_pk_fma_f32 v[74:75], v[74:75], 0.5, v[226:227] op_sel_hi:[1, 0, 1]
	v_pk_fma_f32 v[96:97], v[96:97], 0.5, v[216:217] op_sel_hi:[1, 0, 1]
	v_pk_fma_f32 v[92:93], v[92:93], 0.5, v[220:221] op_sel_hi:[1, 0, 1]
	v_pk_fma_f32 v[80:81], v[80:81], 0.5, v[224:225] op_sel_hi:[1, 0, 1]
	v_pk_fma_f32 v[76:77], v[76:77], 0.5, v[228:229] op_sel_hi:[1, 0, 1]
	v_cvt_pk_bf16_f32 v94, v94, v95
	v_cvt_pk_bf16_f32 v95, v96, v97
	global_store_dwordx2 v[162:163], v[94:95], off
	v_cvt_pk_bf16_f32 v90, v90, v91
	v_cvt_pk_bf16_f32 v91, v92, v93
	global_store_dwordx2 v[162:163], v[90:91], off offset:32
	v_cvt_pk_bf16_f32 v78, v78, v79
	v_cvt_pk_bf16_f32 v79, v80, v81
	global_store_dwordx2 v[162:163], v[78:79], off offset:256
	v_cvt_pk_bf16_f32 v74, v74, v75
	v_cvt_pk_bf16_f32 v75, v76, v77
	v_pk_fma_f32 v[88:89], v[88:89], 0.5, v[232:233] op_sel_hi:[1, 0, 1]
	v_pk_fma_f32 v[86:87], v[86:87], 0.5, v[230:231] op_sel_hi:[1, 0, 1]
	v_pk_fma_f32 v[70:71], v[70:71], 0.5, v[238:239] op_sel_hi:[1, 0, 1]
	v_pk_fma_f32 v[66:67], v[66:67], 0.5, v[246:247] op_sel_hi:[1, 0, 1]
	global_store_dwordx2 v[162:163], v[74:75], off offset:288
	v_cvt_pk_bf16_f32 v74, v86, v87
	v_cvt_pk_bf16_f32 v75, v88, v89
	v_pk_fma_f32 v[84:85], v[84:85], 0.5, v[236:237] op_sel_hi:[1, 0, 1]
	v_pk_fma_f32 v[82:83], v[82:83], 0.5, v[234:235] op_sel_hi:[1, 0, 1]
	v_pk_fma_f32 v[72:73], v[72:73], 0.5, v[240:241] op_sel_hi:[1, 0, 1]
	v_pk_fma_f32 v[68:69], v[68:69], 0.5, v[248:249] op_sel_hi:[1, 0, 1]
	global_store_dwordx2 v[158:159], v[74:75], off
	v_cvt_pk_bf16_f32 v74, v82, v83
	v_cvt_pk_bf16_f32 v75, v84, v85
	global_store_dwordx2 v[158:159], v[74:75], off offset:32
	v_cvt_pk_bf16_f32 v70, v70, v71
	v_cvt_pk_bf16_f32 v71, v72, v73
	global_store_dwordx2 v[158:159], v[70:71], off offset:256
	v_cvt_pk_bf16_f32 v66, v66, v67
	v_cvt_pk_bf16_f32 v67, v68, v69
	global_store_dwordx2 v[158:159], v[66:67], off offset:288
	v_add_u32_e32 v98, 0x48000, v142
	global_load_dwordx4 v[66:69], v[164:165], off
	global_load_dwordx4 v[70:73], v[164:165], off offset:64
	global_load_dwordx4 v[74:77], v[164:165], off offset:512
	global_load_dwordx4 v[78:81], v[164:165], off offset:576
	v_ashrrev_i32_e32 v99, 31, v98
	v_lshl_add_u64 v[94:95], v[98:99], 2, s[36:37]
	global_load_dwordx4 v[82:85], v[94:95], off
	global_load_dwordx4 v[86:89], v[94:95], off offset:64
	global_load_dwordx4 v[90:93], v[94:95], off offset:512
	s_nop 0
	global_load_dwordx4 v[94:97], v[94:95], off offset:576
	v_lshl_add_u64 v[102:103], v[160:161], 1, s[74:75]
	v_add_u32_e32 v100, 0x50000, v142
	v_lshl_add_u64 v[98:99], v[98:99], 1, s[74:75]
	v_ashrrev_i32_e32 v101, 31, v100
	v_lshl_add_u64 v[104:105], v[100:101], 2, s[36:37]
	v_add_u32_e32 v250, 0x58000, v142
	v_ashrrev_i32_e32 v251, 31, v250
	v_lshl_add_u64 v[250:251], v[250:251], 2, s[36:37]
	global_load_dwordx4 v[214:217], v[104:105], off
	global_load_dwordx4 v[218:221], v[104:105], off offset:64
	global_load_dwordx4 v[222:225], v[104:105], off offset:512
	global_load_dwordx4 v[226:229], v[104:105], off offset:576
	global_load_dwordx4 v[230:233], v[250:251], off
	global_load_dwordx4 v[234:237], v[250:251], off offset:64
	global_load_dwordx4 v[238:241], v[250:251], off offset:512
	global_load_dwordx4 v[246:249], v[250:251], off offset:576
	s_waitcnt vmcnt(8)
; __device__ __forceinline__ unsigned cvtpk(float lo, float hi) { unsigned r; asm volatile("v_cvt_pk_bf16_f32 %0, %1, %2" : "=v"(r) : "v"(lo), "v"(hi)); return r; }
;     __device__ __forceinline__ void operator()(const f32x4 (&acc)[2][2][4][2], const Unit& u, int wr, int wc, int fr, int fq) const {
;         const int row0 = u.pm * 256 + wr * 64 + fr, col0 = u.pn * 256 + wc * 32 + 4 * fq;
; #pragma unroll
;         for (int ai = 0; ai < 2; ++ai)
; #pragma unroll
;             for (int mp = 0; mp < 4; mp += 2) {
;                 f32x4 bv[2][2][2];
; #pragma unroll
;                 for (int m = 0; m < 2; ++m) { const int off = (row0 + ai * HALF + (mp + m) * 16) * DM + col0;
; #pragma unroll
;                     for (int bj = 0; bj < 2; ++bj)
; #pragma unroll
;                         for (int n = 0; n < 2; ++n) bv[m][bj][n] = *(const f32x4*)(base + off + bj * HALF + n * 16); }
; #pragma unroll
;                 for (int m = 0; m < 2; ++m) { const int off = (row0 + ai * HALF + (mp + m) * 16) * DM + col0;
; #pragma unroll
;                     for (int bj = 0; bj < 2; ++bj)
; #pragma unroll
;                         for (int n = 0; n < 2; ++n) { const f32x4 v = bv[m][bj][n] + acc[ai][bj][mp + m][n] * s;
;                             u32x2 w; w.x = cvtpk(v[0], v[1]); w.y = cvtpk(v[2], v[3]); *(u32x2*)(xb + off + bj * HALF + n * 16) = w; } }
;                 asm volatile("" ::: "memory"); }
	v_pk_fma_f32 v[62:63], v[62:63], 0.5, v[66:67] op_sel_hi:[1,0,1]
	v_pk_fma_f32 v[58:59], v[58:59], 0.5, v[70:71] op_sel_hi:[1,0,1]
	v_pk_fma_f32 v[46:47], v[46:47], 0.5, v[74:75] op_sel_hi:[1,0,1]
	v_pk_fma_f32 v[42:43], v[42:43], 0.5, v[78:79] op_sel_hi:[1,0,1]
	v_pk_fma_f32 v[64:65], v[64:65], 0.5, v[68:69] op_sel_hi:[1,0,1]
	v_pk_fma_f32 v[60:61], v[60:61], 0.5, v[72:73] op_sel_hi:[1,0,1]
	v_pk_fma_f32 v[48:49], v[48:49], 0.5, v[76:77] op_sel_hi:[1,0,1]
	v_pk_fma_f32 v[44:45], v[44:45], 0.5, v[80:81] op_sel_hi:[1,0,1]
	v_cvt_pk_bf16_f32 v62, v62, v63
	v_cvt_pk_bf16_f32 v63, v64, v65
	global_store_dwordx2 v[102:103], v[62:63], off
	v_cvt_pk_bf16_f32 v58, v58, v59
	v_cvt_pk_bf16_f32 v59, v60, v61
	global_store_dwordx2 v[102:103], v[58:59], off offset:32
	v_cvt_pk_bf16_f32 v46, v46, v47
	v_cvt_pk_bf16_f32 v47, v48, v49
	global_store_dwordx2 v[102:103], v[46:47], off offset:256
	v_cvt_pk_bf16_f32 v42, v42, v43
	v_cvt_pk_bf16_f32 v43, v44, v45
	v_pk_fma_f32 v[56:57], v[56:57], 0.5, v[84:85] op_sel_hi:[1,0,1]
	v_pk_fma_f32 v[54:55], v[54:55], 0.5, v[82:83] op_sel_hi:[1,0,1]
	v_pk_fma_f32 v[38:39], v[38:39], 0.5, v[90:91] op_sel_hi:[1,0,1]
	v_pk_fma_f32 v[34:35], v[34:35], 0.5, v[94:95] op_sel_hi:[1,0,1]
	global_store_dwordx2 v[102:103], v[42:43], off offset:288
	v_cvt_pk_bf16_f32 v42, v54, v55
	v_cvt_pk_bf16_f32 v43, v56, v57
	v_pk_fma_f32 v[52:53], v[52:53], 0.5, v[88:89] op_sel_hi:[1,0,1]
	v_pk_fma_f32 v[50:51], v[50:51], 0.5, v[86:87] op_sel_hi:[1,0,1]
	v_pk_fma_f32 v[40:41], v[40:41], 0.5, v[92:93] op_sel_hi:[1,0,1]
	v_pk_fma_f32 v[36:37], v[36:37], 0.5, v[96:97] op_sel_hi:[1,0,1]
	global_store_dwordx2 v[98:99], v[42:43], off
	v_cvt_pk_bf16_f32 v42, v50, v51
	v_cvt_pk_bf16_f32 v43, v52, v53
	global_store_dwordx2 v[98:99], v[42:43], off offset:32
	v_cvt_pk_bf16_f32 v38, v38, v39
	v_cvt_pk_bf16_f32 v39, v40, v41
	global_store_dwordx2 v[98:99], v[38:39], off offset:256
	v_cvt_pk_bf16_f32 v34, v34, v35
	v_cvt_pk_bf16_f32 v35, v36, v37
	global_store_dwordx2 v[98:99], v[34:35], off offset:288
	v_add_u32_e32 v66, 0x58000, v142
	v_ashrrev_i32_e32 v67, 31, v66
	v_lshl_add_u64 v[62:63], v[66:67], 2, s[36:37]
	s_nop 0
	v_lshl_add_u64 v[68:69], v[100:101], 1, s[74:75]
	v_lshl_add_u64 v[66:67], v[66:67], 1, s[74:75]
	s_waitcnt vmcnt(8)
	v_pk_fma_f32 v[30:31], v[30:31], 0.5, v[214:215] op_sel_hi:[1, 0, 1]
	v_pk_fma_f32 v[26:27], v[26:27], 0.5, v[218:219] op_sel_hi:[1, 0, 1]
	v_pk_fma_f32 v[14:15], v[14:15], 0.5, v[222:223] op_sel_hi:[1, 0, 1]
	v_pk_fma_f32 v[10:11], v[10:11], 0.5, v[226:227] op_sel_hi:[1, 0, 1]
	v_pk_fma_f32 v[32:33], v[32:33], 0.5, v[216:217] op_sel_hi:[1, 0, 1]
	v_pk_fma_f32 v[28:29], v[28:29], 0.5, v[220:221] op_sel_hi:[1, 0, 1]
	v_pk_fma_f32 v[16:17], v[16:17], 0.5, v[224:225] op_sel_hi:[1, 0, 1]
	v_pk_fma_f32 v[12:13], v[12:13], 0.5, v[228:229] op_sel_hi:[1, 0, 1]
	v_cvt_pk_bf16_f32 v30, v30, v31
	v_cvt_pk_bf16_f32 v31, v32, v33
	global_store_dwordx2 v[68:69], v[30:31], off
	v_cvt_pk_bf16_f32 v26, v26, v27
	v_cvt_pk_bf16_f32 v27, v28, v29
	global_store_dwordx2 v[68:69], v[26:27], off offset:32
	v_cvt_pk_bf16_f32 v14, v14, v15
	v_cvt_pk_bf16_f32 v15, v16, v17
	global_store_dwordx2 v[68:69], v[14:15], off offset:256
	v_cvt_pk_bf16_f32 v10, v10, v11
	v_cvt_pk_bf16_f32 v11, v12, v13
	v_pk_fma_f32 v[24:25], v[24:25], 0.5, v[232:233] op_sel_hi:[1, 0, 1]
	v_pk_fma_f32 v[22:23], v[22:23], 0.5, v[230:231] op_sel_hi:[1, 0, 1]
	v_pk_fma_f32 v[6:7], v[6:7], 0.5, v[238:239] op_sel_hi:[1, 0, 1]
	v_pk_fma_f32 v[2:3], v[2:3], 0.5, v[246:247] op_sel_hi:[1, 0, 1]
	global_store_dwordx2 v[68:69], v[10:11], off offset:288
	v_cvt_pk_bf16_f32 v10, v22, v23
	v_cvt_pk_bf16_f32 v11, v24, v25
	v_pk_fma_f32 v[20:21], v[20:21], 0.5, v[236:237] op_sel_hi:[1, 0, 1]
	v_pk_fma_f32 v[18:19], v[18:19], 0.5, v[234:235] op_sel_hi:[1, 0, 1]
	v_pk_fma_f32 v[8:9], v[8:9], 0.5, v[240:241] op_sel_hi:[1, 0, 1]
	v_pk_fma_f32 v[4:5], v[4:5], 0.5, v[248:249] op_sel_hi:[1, 0, 1]
	global_store_dwordx2 v[66:67], v[10:11], off
	v_cvt_pk_bf16_f32 v10, v18, v19
	v_cvt_pk_bf16_f32 v11, v20, v21
	global_store_dwordx2 v[66:67], v[10:11], off offset:32
	v_cvt_pk_bf16_f32 v6, v6, v7
	v_cvt_pk_bf16_f32 v7, v8, v9
	global_store_dwordx2 v[66:67], v[6:7], off offset:256
	v_cvt_pk_bf16_f32 v2, v2, v3
	v_cvt_pk_bf16_f32 v3, v4, v5
	global_store_dwordx2 v[66:67], v[2:3], off offset:288
	s_cbranch_vccz .LBB0_203
	s_waitcnt vmcnt(0)
	s_cmpk_gt_u32 s3, 0xff
	s_cbranch_scc1 .LBB0_218
	s_barrier
